# v25 + nt hint also on the final f32 output stores (write-through, never re-read by the kernel)
# speedup vs baseline: 1.0052x; 1.0052x over previous
; __device__ __forceinline__ float ss_val(u64 v) { return (float)v * (1.0f / 1099511627776.0f); }
; __global__ void __launch_bounds__(NTHREADS, 2) fwd(Args a) {
;     ...
;                 const float rs = __builtin_amdgcn_rsqf(ss_val(sv[r2]) * (1.f / D) + EPS);
;                 f32x4* orow = (f32x4*)(outb + (size_t)(r2 ? m1 : m) * D);
; #pragma unroll
;                 for (int j = 0; j < 2; ++j) {
;                     const u32x4 x4 = xv[r2][j]; const f32x4 w0 = wv[j][0], w1 = wv[j][1];
;                     f32x4 o0, o1;
;                     o0[0] = bf_lo(x4[0]) * rs * w0[0]; o0[1] = bf_hi(x4[0]) * rs * w0[1]; o0[2] = bf_lo(x4[1]) * rs * w0[2]; o0[3] = bf_hi(x4[1]) * rs * w0[3];
;                     o1[0] = bf_lo(x4[2]) * rs * w1[0]; o1[1] = bf_hi(x4[2]) * rs * w1[1]; o1[2] = bf_lo(x4[3]) * rs * w1[2]; o1[3] = bf_hi(x4[3]) * rs * w1[3];
;                     orow[2 * (lane + 64 * j)] = o0; orow[2 * (lane + 64 * j) + 1] = o1;
.Lfn_a_p:
	s_lshl_b32 s18, s38, 12
	s_add_u32 s18, s4, s18
	s_addc_u32 s19, s5, 0
	v_cvt_f32_u32_e32 v66, v24
	v_cvt_f32_u32_e32 v67, v25
	v_fmamk_f32 v66, v67, 0x4f800000, v66
	v_fmamk_f32 v66, v66, 0x26800000, v4
	v_rsq_f32_e32 v64, v66
	v_lshlrev_b32_e32 v60, 16, v26
	v_and_b32_e32 v61, 0xffff0000, v26
	v_lshlrev_b32_e32 v62, 16, v27
	v_and_b32_e32 v63, 0xffff0000, v27
	v_pk_mul_f32 v[60:61], v[64:65], v[60:61] op_sel_hi:[0,1]
	v_pk_mul_f32 v[62:63], v[64:65], v[62:63] op_sel_hi:[0,1]
	v_pk_mul_f32 v[68:69], v[8:9], v[60:61]
	v_pk_mul_f32 v[70:71], v[10:11], v[62:63]
	global_store_dwordx4 v3, v[68:71], s[18:19] offset:0 sc0 sc1 nt
	v_lshlrev_b32_e32 v60, 16, v28
	v_and_b32_e32 v61, 0xffff0000, v28
	v_lshlrev_b32_e32 v62, 16, v29
	v_and_b32_e32 v63, 0xffff0000, v29
	v_pk_mul_f32 v[60:61], v[64:65], v[60:61] op_sel_hi:[0,1]
	v_pk_mul_f32 v[62:63], v[64:65], v[62:63] op_sel_hi:[0,1]
	v_pk_mul_f32 v[72:73], v[12:13], v[60:61]
	v_pk_mul_f32 v[74:75], v[14:15], v[62:63]
	global_store_dwordx4 v3, v[72:75], s[18:19] offset:1024 sc0 sc1 nt
	v_lshlrev_b32_e32 v60, 16, v30
	v_and_b32_e32 v61, 0xffff0000, v30
	v_lshlrev_b32_e32 v62, 16, v31
	v_and_b32_e32 v63, 0xffff0000, v31
	v_pk_mul_f32 v[60:61], v[64:65], v[60:61] op_sel_hi:[0,1]
	v_pk_mul_f32 v[62:63], v[64:65], v[62:63] op_sel_hi:[0,1]
	v_pk_mul_f32 v[76:77], v[16:17], v[60:61]
	v_pk_mul_f32 v[78:79], v[18:19], v[62:63]
	global_store_dwordx4 v3, v[76:79], s[18:19] offset:2048 sc0 sc1 nt
	v_lshlrev_b32_e32 v60, 16, v32
	v_and_b32_e32 v61, 0xffff0000, v32
	v_lshlrev_b32_e32 v62, 16, v33
	v_and_b32_e32 v63, 0xffff0000, v33
	v_pk_mul_f32 v[60:61], v[64:65], v[60:61] op_sel_hi:[0,1]
	v_pk_mul_f32 v[62:63], v[64:65], v[62:63] op_sel_hi:[0,1]
	v_pk_mul_f32 v[80:81], v[20:21], v[60:61]
	v_pk_mul_f32 v[82:83], v[22:23], v[62:63]
	global_store_dwordx4 v3, v[80:83], s[18:19] offset:3072 sc0 sc1 nt
	s_add_u32 s38, s38, s36
	s_cmp_lt_u32 s38, 0x1000
	s_cbranch_scc0 .LBB0_1445

; __device__ __forceinline__ float ss_val(u64 v) { return (float)v * (1.0f / 1099511627776.0f); }
; __global__ void __launch_bounds__(NTHREADS, 2) fwd(Args a) {
;     ...
;                 const float rs = __builtin_amdgcn_rsqf(ss_val(sv[r2]) * (1.f / D) + EPS);
;                 f32x4* orow = (f32x4*)(outb + (size_t)(r2 ? m1 : m) * D);
; #pragma unroll
;                 for (int j = 0; j < 2; ++j) {
;                     const u32x4 x4 = xv[r2][j]; const f32x4 w0 = wv[j][0], w1 = wv[j][1];
;                     f32x4 o0, o1;
;                     o0[0] = bf_lo(x4[0]) * rs * w0[0]; o0[1] = bf_hi(x4[0]) * rs * w0[1]; o0[2] = bf_lo(x4[1]) * rs * w0[2]; o0[3] = bf_hi(x4[1]) * rs * w0[3];
;                     o1[0] = bf_lo(x4[2]) * rs * w1[0]; o1[1] = bf_hi(x4[2]) * rs * w1[1]; o1[2] = bf_lo(x4[3]) * rs * w1[2]; o1[3] = bf_hi(x4[3]) * rs * w1[3];
;                     orow[2 * (lane + 64 * j)] = o0; orow[2 * (lane + 64 * j) + 1] = o1;
.Lfn_b_p:
	s_lshl_b32 s18, s38, 12
	s_add_u32 s18, s4, s18
	s_addc_u32 s19, s5, 0
	v_cvt_f32_u32_e32 v66, v36
	v_cvt_f32_u32_e32 v67, v37
	v_fmamk_f32 v66, v67, 0x4f800000, v66
	v_fmamk_f32 v66, v66, 0x26800000, v4
	v_rsq_f32_e32 v64, v66
	v_lshlrev_b32_e32 v60, 16, v38
	v_and_b32_e32 v61, 0xffff0000, v38
	v_lshlrev_b32_e32 v62, 16, v39
	v_and_b32_e32 v63, 0xffff0000, v39
	v_pk_mul_f32 v[60:61], v[64:65], v[60:61] op_sel_hi:[0,1]
	v_pk_mul_f32 v[62:63], v[64:65], v[62:63] op_sel_hi:[0,1]
	v_pk_mul_f32 v[68:69], v[8:9], v[60:61]
	v_pk_mul_f32 v[70:71], v[10:11], v[62:63]
	global_store_dwordx4 v3, v[68:71], s[18:19] offset:0 sc0 sc1 nt
	v_lshlrev_b32_e32 v60, 16, v40
	v_and_b32_e32 v61, 0xffff0000, v40
	v_lshlrev_b32_e32 v62, 16, v41
	v_and_b32_e32 v63, 0xffff0000, v41
	v_pk_mul_f32 v[60:61], v[64:65], v[60:61] op_sel_hi:[0,1]
	v_pk_mul_f32 v[62:63], v[64:65], v[62:63] op_sel_hi:[0,1]
	v_pk_mul_f32 v[72:73], v[12:13], v[60:61]
	v_pk_mul_f32 v[74:75], v[14:15], v[62:63]
	global_store_dwordx4 v3, v[72:75], s[18:19] offset:1024 sc0 sc1 nt
	v_lshlrev_b32_e32 v60, 16, v42
	v_and_b32_e32 v61, 0xffff0000, v42
	v_lshlrev_b32_e32 v62, 16, v43
	v_and_b32_e32 v63, 0xffff0000, v43
	v_pk_mul_f32 v[60:61], v[64:65], v[60:61] op_sel_hi:[0,1]
	v_pk_mul_f32 v[62:63], v[64:65], v[62:63] op_sel_hi:[0,1]
	v_pk_mul_f32 v[76:77], v[16:17], v[60:61]
	v_pk_mul_f32 v[78:79], v[18:19], v[62:63]
	global_store_dwordx4 v3, v[76:79], s[18:19] offset:2048 sc0 sc1 nt
	v_lshlrev_b32_e32 v60, 16, v44
	v_and_b32_e32 v61, 0xffff0000, v44
	v_lshlrev_b32_e32 v62, 16, v45
	v_and_b32_e32 v63, 0xffff0000, v45
	v_pk_mul_f32 v[60:61], v[64:65], v[60:61] op_sel_hi:[0,1]
	v_pk_mul_f32 v[62:63], v[64:65], v[62:63] op_sel_hi:[0,1]
	v_pk_mul_f32 v[80:81], v[20:21], v[60:61]
	v_pk_mul_f32 v[82:83], v[22:23], v[62:63]
	global_store_dwordx4 v3, v[80:83], s[18:19] offset:3072 sc0 sc1 nt
	s_add_u32 s38, s38, s36
	s_cmp_lt_u32 s38, 0x1000
	s_cbranch_scc0 .LBB0_1445

; __device__ __forceinline__ float ss_val(u64 v) { return (float)v * (1.0f / 1099511627776.0f); }
; __global__ void __launch_bounds__(NTHREADS, 2) fwd(Args a) {
;     ...
;                 const float rs = __builtin_amdgcn_rsqf(ss_val(sv[r2]) * (1.f / D) + EPS);
;                 f32x4* orow = (f32x4*)(outb + (size_t)(r2 ? m1 : m) * D);
; #pragma unroll
;                 for (int j = 0; j < 2; ++j) {
;                     const u32x4 x4 = xv[r2][j]; const f32x4 w0 = wv[j][0], w1 = wv[j][1];
;                     f32x4 o0, o1;
;                     o0[0] = bf_lo(x4[0]) * rs * w0[0]; o0[1] = bf_hi(x4[0]) * rs * w0[1]; o0[2] = bf_lo(x4[1]) * rs * w0[2]; o0[3] = bf_hi(x4[1]) * rs * w0[3];
;                     o1[0] = bf_lo(x4[2]) * rs * w1[0]; o1[1] = bf_hi(x4[2]) * rs * w1[1]; o1[2] = bf_lo(x4[3]) * rs * w1[2]; o1[3] = bf_hi(x4[3]) * rs * w1[3];
;                     orow[2 * (lane + 64 * j)] = o0; orow[2 * (lane + 64 * j) + 1] = o1;
.Lfn_c_p:
	s_lshl_b32 s18, s38, 12
	s_add_u32 s18, s4, s18
	s_addc_u32 s19, s5, 0
	v_cvt_f32_u32_e32 v66, v48
	v_cvt_f32_u32_e32 v67, v49
	v_fmamk_f32 v66, v67, 0x4f800000, v66
	v_fmamk_f32 v66, v66, 0x26800000, v4
	v_rsq_f32_e32 v64, v66
	v_lshlrev_b32_e32 v60, 16, v50
	v_and_b32_e32 v61, 0xffff0000, v50
	v_lshlrev_b32_e32 v62, 16, v51
	v_and_b32_e32 v63, 0xffff0000, v51
	v_pk_mul_f32 v[60:61], v[64:65], v[60:61] op_sel_hi:[0,1]
	v_pk_mul_f32 v[62:63], v[64:65], v[62:63] op_sel_hi:[0,1]
	v_pk_mul_f32 v[68:69], v[8:9], v[60:61]
	v_pk_mul_f32 v[70:71], v[10:11], v[62:63]
	global_store_dwordx4 v3, v[68:71], s[18:19] offset:0 sc0 sc1 nt
	v_lshlrev_b32_e32 v60, 16, v52
	v_and_b32_e32 v61, 0xffff0000, v52
	v_lshlrev_b32_e32 v62, 16, v53
	v_and_b32_e32 v63, 0xffff0000, v53
	v_pk_mul_f32 v[60:61], v[64:65], v[60:61] op_sel_hi:[0,1]
	v_pk_mul_f32 v[62:63], v[64:65], v[62:63] op_sel_hi:[0,1]
	v_pk_mul_f32 v[72:73], v[12:13], v[60:61]
	v_pk_mul_f32 v[74:75], v[14:15], v[62:63]
	global_store_dwordx4 v3, v[72:75], s[18:19] offset:1024 sc0 sc1 nt
	v_lshlrev_b32_e32 v60, 16, v54
	v_and_b32_e32 v61, 0xffff0000, v54
	v_lshlrev_b32_e32 v62, 16, v55
	v_and_b32_e32 v63, 0xffff0000, v55
	v_pk_mul_f32 v[60:61], v[64:65], v[60:61] op_sel_hi:[0,1]
	v_pk_mul_f32 v[62:63], v[64:65], v[62:63] op_sel_hi:[0,1]
	v_pk_mul_f32 v[76:77], v[16:17], v[60:61]
	v_pk_mul_f32 v[78:79], v[18:19], v[62:63]
	global_store_dwordx4 v3, v[76:79], s[18:19] offset:2048 sc0 sc1 nt
	v_lshlrev_b32_e32 v60, 16, v56
	v_and_b32_e32 v61, 0xffff0000, v56
	v_lshlrev_b32_e32 v62, 16, v57
	v_and_b32_e32 v63, 0xffff0000, v57
	v_pk_mul_f32 v[60:61], v[64:65], v[60:61] op_sel_hi:[0,1]
	v_pk_mul_f32 v[62:63], v[64:65], v[62:63] op_sel_hi:[0,1]
	v_pk_mul_f32 v[80:81], v[20:21], v[60:61]
	v_pk_mul_f32 v[82:83], v[22:23], v[62:63]
	global_store_dwordx4 v3, v[80:83], s[18:19] offset:3072 sc0 sc1 nt
	s_add_u32 s38, s38, s36
	s_cmp_lt_u32 s38, 0x1000
	s_cbranch_scc0 .LBB0_1445

; __device__ __forceinline__ float ss_val(u64 v) { return (float)v * (1.0f / 1099511627776.0f); }
; __global__ void __launch_bounds__(NTHREADS, 2) fwd(Args a) {
;     ...
;                 const float rs = __builtin_amdgcn_rsqf(ss_val(sv[r2]) * (1.f / D) + EPS);
;                 f32x4* orow = (f32x4*)(outb + (size_t)(r2 ? m1 : m) * D);
; #pragma unroll
;                 for (int j = 0; j < 2; ++j) {
;                     const u32x4 x4 = xv[r2][j]; const f32x4 w0 = wv[j][0], w1 = wv[j][1];
;                     f32x4 o0, o1;
;                     o0[0] = bf_lo(x4[0]) * rs * w0[0]; o0[1] = bf_hi(x4[0]) * rs * w0[1]; o0[2] = bf_lo(x4[1]) * rs * w0[2]; o0[3] = bf_hi(x4[1]) * rs * w0[3];
;                     o1[0] = bf_lo(x4[2]) * rs * w1[0]; o1[1] = bf_hi(x4[2]) * rs * w1[1]; o1[2] = bf_lo(x4[3]) * rs * w1[2]; o1[3] = bf_hi(x4[3]) * rs * w1[3];
;                     orow[2 * (lane + 64 * j)] = o0; orow[2 * (lane + 64 * j) + 1] = o1;
.Lfn_e_p:
	s_lshl_b32 s18, s38, 12
	s_add_u32 s18, s4, s18
	s_addc_u32 s19, s5, 0
	v_cvt_f32_u32_e32 v66, v36
	v_cvt_f32_u32_e32 v67, v37
	v_fmamk_f32 v66, v67, 0x4f800000, v66
	v_fmamk_f32 v66, v66, 0x26800000, v4
	v_rsq_f32_e32 v64, v66
	v_lshlrev_b32_e32 v60, 16, v38
	v_and_b32_e32 v61, 0xffff0000, v38
	v_lshlrev_b32_e32 v62, 16, v39
	v_and_b32_e32 v63, 0xffff0000, v39
	v_pk_mul_f32 v[60:61], v[64:65], v[60:61] op_sel_hi:[0,1]
	v_pk_mul_f32 v[62:63], v[64:65], v[62:63] op_sel_hi:[0,1]
	v_pk_mul_f32 v[68:69], v[8:9], v[60:61]
	v_pk_mul_f32 v[70:71], v[10:11], v[62:63]
	global_store_dwordx4 v3, v[68:71], s[18:19] offset:0 sc0 sc1 nt
	v_lshlrev_b32_e32 v60, 16, v40
	v_and_b32_e32 v61, 0xffff0000, v40
	v_lshlrev_b32_e32 v62, 16, v41
	v_and_b32_e32 v63, 0xffff0000, v41
	v_pk_mul_f32 v[60:61], v[64:65], v[60:61] op_sel_hi:[0,1]
	v_pk_mul_f32 v[62:63], v[64:65], v[62:63] op_sel_hi:[0,1]
	v_pk_mul_f32 v[72:73], v[12:13], v[60:61]
	v_pk_mul_f32 v[74:75], v[14:15], v[62:63]
	global_store_dwordx4 v3, v[72:75], s[18:19] offset:1024 sc0 sc1 nt
	v_lshlrev_b32_e32 v60, 16, v42
	v_and_b32_e32 v61, 0xffff0000, v42
	v_lshlrev_b32_e32 v62, 16, v43
	v_and_b32_e32 v63, 0xffff0000, v43
	v_pk_mul_f32 v[60:61], v[64:65], v[60:61] op_sel_hi:[0,1]
	v_pk_mul_f32 v[62:63], v[64:65], v[62:63] op_sel_hi:[0,1]
	v_pk_mul_f32 v[76:77], v[16:17], v[60:61]
	v_pk_mul_f32 v[78:79], v[18:19], v[62:63]
	global_store_dwordx4 v3, v[76:79], s[18:19] offset:2048 sc0 sc1 nt
	v_lshlrev_b32_e32 v60, 16, v44
	v_and_b32_e32 v61, 0xffff0000, v44
	v_lshlrev_b32_e32 v62, 16, v45
	v_and_b32_e32 v63, 0xffff0000, v45
	v_pk_mul_f32 v[60:61], v[64:65], v[60:61] op_sel_hi:[0,1]
	v_pk_mul_f32 v[62:63], v[64:65], v[62:63] op_sel_hi:[0,1]
	v_pk_mul_f32 v[80:81], v[20:21], v[60:61]
	v_pk_mul_f32 v[82:83], v[22:23], v[62:63]
	global_store_dwordx4 v3, v[80:83], s[18:19] offset:3072 sc0 sc1 nt
	s_add_u32 s38, s38, s36
	s_cmp_lt_u32 s38, 0x1000
	s_cbranch_scc0 .LBB0_1445
	s_branch .Lfn_c
